# baseline (speedup 1.0000x reference)
; DI void row_scales(const float* PS, const pg8::Unit& u, int wr, int lane, float (&rs)[2][4]) {
;     ...
;         const int row = u.pm * 256 + ai * 128 + wr * 64 + lane;
;         float v = 1.f;
;         if (row < MPROMPT) {
;             const f32x4* p = (const f32x4*)(PS + (size_t)row * 32);
;             f32x4 s = p[0];
; #pragma unroll
;             for (int j = 1; j < 8; ++j) s = s + p[j];
;             v = 1.0f / sqrtf(((s.x + s.y) + (s.z + s.w)) * (1.0f / DM) + 1e-6f);
;         }
;         r2[ai] = v;
.LBB0_163:
	s_lshl_b32 s6, s38, 8
	v_add_u32_e32 v146, s6, v163
	v_cmp_gt_i32_e32 vcc, s26, v146
	v_mov_b32_e32 v148, 1.0
	v_mov_b32_e32 v149, 1.0
	s_and_saveexec_b64 s[42:43], vcc
	s_cbranch_execz .LBB0_165
	v_ashrrev_i32_e32 v147, 31, v146
	v_lshlrev_b64 v[150:151], 7, v[146:147]
	v_lshl_add_u64 v[158:159], s[86:87], 0, v[150:151]
	global_load_dwordx4 v[150:153], v[158:159], off offset:48
	global_load_dwordx4 v[154:157], v[158:159], off offset:32
	global_load_dwordx4 v[164:167], v[158:159], off
	global_load_dwordx4 v[168:171], v[158:159], off offset:16
	global_load_dwordx4 v[194:197], v[158:159], off offset:112
	global_load_dwordx4 v[198:201], v[158:159], off offset:96
	global_load_dwordx4 v[202:205], v[158:159], off offset:80
	global_load_dwordx4 v[206:209], v[158:159], off offset:64
	s_waitcnt vmcnt(4)
	v_pk_add_f32 v[166:167], v[166:167], v[170:171]
	v_pk_add_f32 v[164:165], v[164:165], v[168:169]
	v_pk_add_f32 v[156:157], v[166:167], v[156:157]
	v_pk_add_f32 v[154:155], v[164:165], v[154:155]
	v_pk_add_f32 v[172:173], v[156:157], v[152:153]
	v_pk_add_f32 v[174:175], v[154:155], v[150:151]
	s_waitcnt vmcnt(0)
	v_pk_add_f32 v[158:159], v[172:173], v[208:209]
	v_pk_add_f32 v[168:169], v[174:175], v[206:207]
	v_pk_add_f32 v[158:159], v[158:159], v[204:205]
	v_pk_add_f32 v[164:165], v[168:169], v[202:203]
	v_pk_add_f32 v[156:157], v[158:159], v[200:201]
	v_pk_add_f32 v[154:155], v[164:165], v[198:199]
	v_pk_add_f32 v[152:153], v[156:157], v[196:197]
	v_pk_add_f32 v[150:151], v[154:155], v[194:195]
	s_nop 0
	v_pk_mov_b32 v[154:155], v[150:151], v[152:153] op_sel:[1,0]
	v_mov_b32_e32 v151, v153
	v_pk_add_f32 v[150:151], v[154:155], v[150:151]
	s_nop 0
	v_add_f32_e32 v147, v150, v151
	v_fmamk_f32 v147, v147, 0x3a000000, v242
	v_cmp_gt_f32_e32 vcc, s33, v147
	v_mul_f32_e32 v149, 0x4f800000, v147
	s_nop 0
	v_cndmask_b32_e32 v147, v147, v149, vcc
	v_sqrt_f32_e32 v149, v147
	s_nop 0
	v_add_u32_e32 v150, -1, v149
	v_fma_f32 v151, -v150, v149, v147
	v_cmp_ge_f32_e64 s[38:39], 0, v151
	v_add_u32_e32 v151, 1, v149
	s_nop 0
	v_cndmask_b32_e64 v150, v149, v150, s[38:39]
	v_fma_f32 v149, -v151, v149, v147
	v_cmp_lt_f32_e64 s[38:39], 0, v149
	s_nop 1
	v_cndmask_b32_e64 v149, v150, v151, s[38:39]
	v_mul_f32_e32 v150, 0x37800000, v149
	v_cndmask_b32_e32 v149, v149, v150, vcc
	v_cmp_class_f32_e32 vcc, v147, v243
	s_nop 1
	v_cndmask_b32_e32 v147, v149, v147, vcc
	v_div_scale_f32 v149, s[14:15], v147, v147, 1.0
	v_rcp_f32_e32 v150, v149
	s_nop 0
	v_fma_f32 v151, -v149, v150, 1.0
	v_fmac_f32_e32 v150, v151, v150
	v_div_scale_f32 v151, vcc, 1.0, v147, 1.0
	v_mul_f32_e32 v152, v151, v150
	v_fma_f32 v153, -v149, v152, v151
	v_fmac_f32_e32 v152, v153, v150
	v_fma_f32 v149, -v149, v152, v151
	v_div_fmas_f32 v149, v149, v150, v152
	v_div_fixup_f32 v149, v149, v147, 1.0
.LBB0_165:
	s_or_b64 exec, exec, s[42:43]
	v_add_u32_e32 v146, 0x80, v146
	v_cmp_gt_i32_e32 vcc, s26, v146
	s_and_saveexec_b64 s[42:43], vcc
	s_cbranch_execz .LBB0_167
	v_ashrrev_i32_e32 v147, 31, v146
	v_lshlrev_b64 v[146:147], 7, v[146:147]
	v_lshl_add_u64 v[146:147], s[86:87], 0, v[146:147]
	global_load_dwordx4 v[150:153], v[146:147], off offset:48
	global_load_dwordx4 v[154:157], v[146:147], off offset:32
	global_load_dwordx4 v[164:167], v[146:147], off
	global_load_dwordx4 v[168:171], v[146:147], off offset:16
	global_load_dwordx4 v[194:197], v[146:147], off offset:112
	global_load_dwordx4 v[198:201], v[146:147], off offset:96
	global_load_dwordx4 v[202:205], v[146:147], off offset:80
	global_load_dwordx4 v[206:209], v[146:147], off offset:64
	s_waitcnt vmcnt(4)
	v_pk_add_f32 v[158:159], v[166:167], v[170:171]
	v_pk_add_f32 v[164:165], v[164:165], v[168:169]
	v_pk_add_f32 v[156:157], v[158:159], v[156:157]
	v_pk_add_f32 v[154:155], v[164:165], v[154:155]
	v_pk_add_f32 v[158:159], v[156:157], v[152:153]
	v_pk_add_f32 v[172:173], v[154:155], v[150:151]
	s_waitcnt vmcnt(0)
	v_pk_add_f32 v[146:147], v[158:159], v[208:209]
	v_pk_add_f32 v[158:159], v[172:173], v[206:207]
	v_pk_add_f32 v[146:147], v[146:147], v[204:205]
	v_pk_add_f32 v[158:159], v[158:159], v[202:203]
	v_pk_add_f32 v[146:147], v[146:147], v[200:201]
	v_pk_add_f32 v[154:155], v[158:159], v[198:199]
	v_pk_add_f32 v[146:147], v[146:147], v[196:197]
	v_pk_add_f32 v[150:151], v[154:155], v[194:195]
	s_nop 0
	v_pk_mov_b32 v[152:153], v[150:151], v[146:147] op_sel:[1,0]
	v_mov_b32_e32 v151, v147
	v_pk_add_f32 v[146:147], v[152:153], v[150:151]
	s_nop 0
	v_add_f32_e32 v146, v146, v147
	v_fmamk_f32 v146, v146, 0x3a000000, v242
	v_cmp_gt_f32_e32 vcc, s33, v146
	v_mul_f32_e32 v147, 0x4f800000, v146
	s_nop 0
	v_cndmask_b32_e32 v146, v146, v147, vcc
	v_sqrt_f32_e32 v147, v146
	s_nop 0
	v_add_u32_e32 v148, -1, v147
	v_fma_f32 v150, -v148, v147, v146
	v_cmp_ge_f32_e64 s[38:39], 0, v150
	v_add_u32_e32 v150, 1, v147
	s_nop 0
	v_cndmask_b32_e64 v148, v147, v148, s[38:39]
	v_fma_f32 v147, -v150, v147, v146
	v_cmp_lt_f32_e64 s[38:39], 0, v147
	s_nop 1
	v_cndmask_b32_e64 v147, v148, v150, s[38:39]
	v_mul_f32_e32 v148, 0x37800000, v147
	v_cndmask_b32_e32 v147, v147, v148, vcc
	v_cmp_class_f32_e32 vcc, v146, v243
	s_nop 1
	v_cndmask_b32_e32 v146, v147, v146, vcc
	v_div_scale_f32 v147, s[14:15], v146, v146, 1.0
	v_rcp_f32_e32 v148, v147
	s_nop 0
	v_fma_f32 v150, -v147, v148, 1.0
	v_fmac_f32_e32 v148, v150, v148
	v_div_scale_f32 v150, vcc, 1.0, v146, 1.0
	v_mul_f32_e32 v151, v150, v148
	v_fma_f32 v152, -v147, v151, v150
	v_fmac_f32_e32 v151, v152, v148
	v_fma_f32 v147, -v147, v151, v150
	v_div_fmas_f32 v147, v147, v148, v151
	v_div_fixup_f32 v148, v147, v146, 1.0
